# v14 + MLA per-call prologue: the four LDS-resident query fragments loaded together (was four serial load-wait-write round trips)
# baseline (speedup 1.0000x reference)
; __device__ __forceinline__ int v_st(int k, int c) { const int kk = (k & ~0xC) | ((k & 4) << 1) | ((k & 8) >> 1); return ((kk >> 3) * 4 + (c >> 5)) * 512 + ((kk & 7) * 32 + (c & 31)) * 2; }
; __device__ __forceinline__ int v_rd_base(int lane) { return ((lane & 3) << 3) | (((lane >> 2) & 3) << 6) | (((lane >> 4) & 1) << 5) | (((lane >> 5) & 1) << 8); }
; #define SLOAD(i, j) do { const long rb_ = KROW(j); sr_[i].vs0 = *(const bf16x8*)(a.V + (rb_ + sr) * LDV + sc); sr_[i].vs1 = *(const bf16x8*)(a.V + (rb_ + 32 + sr) * LDV + sc); \
;     _Pragma("unroll") for (int c_ = 0; c_ < KCH; ++c_) sr_[i].ks[c_] = *(const bf16x8*)(kptr[c_] + rb_ * kld[c_]); } while (0)
; #define SWRITE(b, i) do { *(bf16x8*)(V_lds + (b) * SHM_V + vst0) = sr_[i].vs0; *(bf16x8*)(V_lds + (b) * SHM_V + vst1) = sr_[i].vs1; \
;     _Pragma("unroll") for (int c_ = 0; c_ < KCH; ++c_) *(bf16x8*)(K_lds + (b) * SHM_K + kwo[c_]) = sr_[i].ks[c_]; } while (0)
; template <int DQK, int DK1, int LDQ, int LDK, int LDKR, int LDV, int NQL, int SDEPTH>
; __device__ __forceinline__ void attn_core(const AttnArgs& a, char* lds, f32x16 (&o)[4]) {
;     ...
;     char* QL = lds + 2 * SHM_V + 2 * SHM_K + 2048 + tid * 16;
;     { const bf16_t* Qw = a.Q + (long)(wid * 32 + r32) * LDQ + hi * 8;
; #pragma unroll
;       for (int d0 = 0; d0 < NQR; ++d0) qr[d0] = *(const bf16x8*)(Qw + d0 * 16);
; #pragma unroll
;       for (int d0 = NQR; d0 < ND0; ++d0) *(bf16x8*)(QL + (d0 - NQR) * 8192) = *(const bf16x8*)(Qw + d0 * 16); }
;     const int sr = tid >> 4, sc = (tid & 15) * 8, vst0 = v_st(sr, sc), vst1 = v_st(32 + sr, sc);
;     const int vb0 = (int)(uintptr_t)V_lds + v_rd_base(lane);
;     const bf16_t* kptr[KCH]; int kld[KCH], kwo[KCH];
; #pragma unroll
;     for (int c = 0; c < KCH; ++c) { const int idx = tid + c * 512, kr_ = idx / CPR, kc = (idx % CPR) * 8;
;         if (kc < DK1) { kptr[c] = a.Kn + (long)kr_ * LDK + kc; kld[c] = LDK; } else { kptr[c] = a.Kr + (long)kr_ * LDKR + (kc - DK1); kld[c] = LDKR; }
;         kwo[c] = kr_ * KP + ((kc * 2) ^ ((kr_ & 7) << 4)); }
;     struct { bf16x8 vs0, vs1, ks[KCH]; } sr_[SDEPTH];
;     int kb[4];
; #pragma unroll
;     for (int m = 0; m < 4; ++m) kb[m] = r32 * KP + ((m * 32 + hi * 16) ^ ((r32 & 7) << 4));
;     ...
;     SLOAD(SE, 0); asm volatile("s_waitcnt vmcnt(0)" ::: "memory"); SWRITE(0, SE); __syncthreads();
.LBB0_206:
	s_and_b32 s24, s14, 7
	s_mul_i32 s15, s23, 0xc00
	s_mul_hi_i32 s14, s23, 0xc00
	s_add_u32 s15, s4, s15
	s_addc_u32 s14, s5, s14
	s_mul_i32 s20, s24, 0x180
	s_add_u32 s20, s15, s20
	v_mov_b32_e32 v9, v159
	s_addc_u32 s21, s14, 0
	s_lshl_b32 s14, s24, 9
	v_ashrrev_i32_e32 v0, 1, v9
	v_bfe_u32 v2, v9, 5, 1
	v_bfi_b32 v3, s33, v0, v9
	v_mov_b64_e32 v[0:1], s[20:21]
	v_lshlrev_b32_e32 v8, 4, v9
	v_mad_i64_i32 v[0:1], s[20:21], v3, s77, v[0:1]
	v_lshlrev_b32_e32 v96, 4, v2
	v_lshl_add_u64 v[4:5], v[0:1], 0, v[96:97]
	v_add_u32_e32 v0, 0, v8
	global_load_dwordx4 v[126:129], v[4:5], off
	global_load_dwordx4 v[122:125], v[4:5], off offset:32
	global_load_dwordx4 v[118:121], v[4:5], off offset:64
	global_load_dwordx4 v[114:117], v[4:5], off offset:96
	global_load_dwordx4 v[110:113], v[4:5], off offset:128
	global_load_dwordx4 v[106:109], v[4:5], off offset:160
	global_load_dwordx4 v[102:105], v[4:5], off offset:192
	global_load_dwordx4 v[98:101], v[4:5], off offset:224
	v_add_u32_e32 v181, 0x14800, v0
	global_load_dwordx4 v[64:67], v[4:5], off offset:256
	global_load_dwordx4 v[68:71], v[4:5], off offset:288
	global_load_dwordx4 v[72:75], v[4:5], off offset:320
	global_load_dwordx4 v[76:79], v[4:5], off offset:352
	s_add_u32 s14, s6, s14
	s_addc_u32 s15, s7, 0
	v_mul_hi_i32 v0, v9, s86
	v_lshrrev_b32_e32 v1, 31, v0
	v_ashrrev_i32_e32 v0, 2, v0
	v_add_u32_e32 v0, v0, v1
	v_mul_lo_u32 v1, v0, 24
	v_sub_u32_e32 v10, v9, v1
	v_lshlrev_b32_e32 v2, 3, v10
	v_cmp_lt_i32_e32 vcc, 15, v10
	v_ashrrev_i32_e32 v1, 31, v0
	s_and_saveexec_b64 s[20:21], vcc
	s_xor_b64 s[20:21], exec, s[20:21]
	v_lshlrev_b64 v[4:5], 7, v[0:1]
	v_lshl_add_u64 v[4:5], s[18:19], 0, v[4:5]
	v_mov_b32_e32 v3, v97
	s_movk_i32 s38, 0xff00
	v_lshl_add_u64 v[2:3], v[2:3], 1, v[4:5]
	s_mov_b32 s39, -1
	v_lshl_add_u64 v[162:163], v[2:3], 0, s[38:39]
	s_or_saveexec_b64 s[20:21], s[20:21]
	v_mov_b64_e32 v[164:165], 64
	s_xor_b64 exec, exec, s[20:21]
	v_lshlrev_b64 v[4:5], 12, v[0:1]
	v_lshl_add_u64 v[4:5], s[14:15], 0, v[4:5]
	v_ashrrev_i32_e32 v3, 31, v2
	v_lshl_add_u64 v[162:163], v[2:3], 1, v[4:5]
	v_mov_b64_e32 v[164:165], 0x800
	s_or_b64 exec, exec, s[20:21]
	v_add_u32_e32 v1, 0x200, v9
	v_mul_hi_i32 v2, v1, s86
	v_lshrrev_b32_e32 v3, 31, v2
	v_ashrrev_i32_e32 v2, 2, v2
	v_add_u32_e32 v4, v2, v3
	v_mul_lo_u32 v2, v4, 24
	v_sub_u32_e32 v11, v1, v2
	v_lshlrev_b32_e32 v2, 3, v11
	v_cmp_lt_i32_e32 vcc, 15, v11
	v_ashrrev_i32_e32 v5, 31, v4
	s_and_saveexec_b64 s[20:21], vcc
	s_xor_b64 s[20:21], exec, s[20:21]
	v_lshlrev_b64 v[6:7], 7, v[4:5]
	v_lshl_add_u64 v[6:7], s[18:19], 0, v[6:7]
	v_mov_b32_e32 v3, v97
	s_movk_i32 s38, 0xff00
	v_lshl_add_u64 v[2:3], v[2:3], 1, v[6:7]
	s_mov_b32 s39, -1
	v_lshl_add_u64 v[166:167], v[2:3], 0, s[38:39]
	s_or_saveexec_b64 s[20:21], s[20:21]
	v_mov_b64_e32 v[168:169], 64
	s_xor_b64 exec, exec, s[20:21]
	v_lshlrev_b64 v[6:7], 12, v[4:5]
	v_lshl_add_u64 v[6:7], s[14:15], 0, v[6:7]
	v_ashrrev_i32_e32 v3, 31, v2
	v_lshl_add_u64 v[166:167], v[2:3], 1, v[6:7]
	v_mov_b64_e32 v[168:169], 0x800
	s_or_b64 exec, exec, s[20:21]
	v_add_u32_e32 v1, 0x400, v9
	v_mul_hi_i32 v2, v1, s86
	v_lshrrev_b32_e32 v3, 31, v2
	v_ashrrev_i32_e32 v2, 2, v2
	v_add_u32_e32 v2, v2, v3
	v_mul_lo_u32 v3, v2, 24
	v_sub_u32_e32 v1, v1, v3
	v_lshlrev_b32_e32 v6, 3, v1
	v_cmp_lt_i32_e32 vcc, 15, v1
	v_ashrrev_i32_e32 v3, 31, v2
	s_and_saveexec_b64 s[20:21], vcc
	s_xor_b64 s[20:21], exec, s[20:21]
	v_lshlrev_b64 v[12:13], 7, v[2:3]
	v_lshl_add_u64 v[12:13], s[18:19], 0, v[12:13]
	v_mov_b32_e32 v7, v97
	s_movk_i32 s38, 0xff00
	v_lshl_add_u64 v[6:7], v[6:7], 1, v[12:13]
	s_mov_b32 s39, -1
	v_lshl_add_u64 v[170:171], v[6:7], 0, s[38:39]
	s_or_saveexec_b64 s[20:21], s[20:21]
	v_mov_b64_e32 v[172:173], 64
	s_xor_b64 exec, exec, s[20:21]
	v_lshlrev_b64 v[12:13], 12, v[2:3]
	v_lshl_add_u64 v[12:13], s[14:15], 0, v[12:13]
	v_ashrrev_i32_e32 v7, 31, v6
	v_lshl_add_u64 v[170:171], v[6:7], 1, v[12:13]
	v_mov_b64_e32 v[172:173], 0x800
	s_or_b64 exec, exec, s[20:21]
	v_mul_lo_u32 v3, v4, s84
	v_bitop3_b32 v4, v4, v11, 7 bitop3:0x6c
	v_ashrrev_i32_e32 v174, 4, v9
	v_lshl_add_u32 v20, v4, 4, v3
	v_and_b32_e32 v4, 0xfffff0, v174
	v_lshlrev_b32_e32 v5, 1, v174
	v_and_or_b32 v4, v5, 8, v4
	v_lshrrev_b32_e32 v5, 1, v174
	v_and_b32_e32 v6, 3, v174
	v_mul_lo_u32 v3, v0, s84
	v_bitop3_b32 v0, v0, v10, 7 bitop3:0x6c
	v_and_or_b32 v5, v5, 4, v6
	v_add_u32_e32 v6, 32, v174
	v_lshl_add_u32 v21, v0, 4, v3
	v_and_b32_e32 v0, 0x3fffffc0, v9
	s_add_i32 s20, 0, 0x14000
	v_and_b32_e32 v7, 0xfffff0, v6
	v_lshlrev_b32_e32 v6, 1, v6
	v_and_b32_e32 v52, 63, v9
	v_lshl_add_u32 v161, v0, 2, s20
	v_lshlrev_b32_e32 v0, 3, v9
	v_and_or_b32 v6, v6, 8, v7
	v_and_b32_e32 v3, 0x78, v0
	v_lshrrev_b32_e32 v4, 1, v4
	v_bfe_u32 v0, v0, 5, 2
	v_lshrrev_b32_e32 v6, 1, v6
	v_lshlrev_b32_e32 v7, 4, v52
	v_and_b32_e32 v51, 31, v9
	v_or_b32_e32 v4, v4, v0
	v_or_b32_e32 v0, v6, v0
	v_lshlrev_b32_e32 v6, 3, v52
	v_and_b32_e32 v7, 0xc0, v7
	v_lshlrev_b32_e32 v9, 1, v52
	v_and_or_b32 v7, v6, 24, v7
	v_and_b32_e32 v9, 32, v9
	v_and_b32_e32 v6, 0x100, v6
	v_or3_b32 v53, v7, v9, v6
	v_mul_lo_u32 v6, v2, s84
	v_bitop3_b32 v1, v2, v1, 7 bitop3:0x6c
	s_lshl_b32 s20, s68, 6
	v_lshlrev_b32_e32 v5, 6, v5
	v_lshlrev_b32_e32 v0, 9, v0
	v_lshl_add_u32 v22, v1, 4, v6
	v_and_b32_e32 v1, 48, v8
	s_sub_i32 s20, s28, s20
	v_or3_b32 v23, v0, v5, v1
	v_mul_u32_u24_e32 v0, 0x180, v51
	v_and_b32_e32 v2, 0x70, v8
	v_or_b32_e32 v6, 32, v96
	s_and_b64 s[12:13], s[12:13], exec
	v_bitop3_b32 v50, v6, v0, v2 bitop3:0xde
	v_or_b32_e32 v6, 64, v96
	s_cselect_b32 s12, s25, s20
	v_ashrrev_i32_e32 v175, 31, v174
	v_lshlrev_b32_e32 v4, 9, v4
	v_bitop3_b32 v62, v6, v0, v2 bitop3:0xde
	v_or_b32_e32 v6, 0x60, v96
	s_ashr_i32 s13, s12, 31
	v_lshl_add_u64 v[176:177], v[174:175], 0, 32
	v_bitop3_b32 v24, v96, v0, v2 bitop3:0xde
	v_bitop3_b32 v63, v6, v0, v2 bitop3:0xde
	v_or3_b32 v25, v4, v5, v1
	v_lshl_add_u64 v[0:1], v[174:175], 0, s[12:13]
	v_lshl_add_u64 v[4:5], v[176:177], 0, s[12:13]
	v_lshlrev_b64 v[0:1], 12, v[0:1]
	v_lshlrev_b64 v[4:5], 12, v[4:5]
	v_lshl_add_u64 v[0:1], s[14:15], 0, v[0:1]
	v_lshlrev_b32_e32 v48, 1, v3
	v_mov_b32_e32 v49, v97
	v_lshl_add_u64 v[4:5], s[14:15], 0, v[4:5]
	v_mad_i64_i32 v[8:9], s[20:21], v164, s12, 0
	v_mad_i64_i32 v[12:13], s[20:21], v168, s12, 0
	v_mad_i64_i32 v[16:17], s[20:21], v172, s12, 0
	v_lshl_add_u64 v[0:1], v[0:1], 0, v[48:49]
	v_lshl_add_u64 v[4:5], v[4:5], 0, v[48:49]
	v_lshl_add_u64 v[8:9], v[8:9], 1, v[162:163]
	v_lshl_add_u64 v[12:13], v[12:13], 1, v[166:167]
	v_lshl_add_u64 v[16:17], v[16:17], 1, v[170:171]
	global_load_dwordx4 v[0:3], v[0:1], off offset:256
	v_add_u32_e32 v186, 0, v25
	global_load_dwordx4 v[4:7], v[4:5], off offset:256
	v_add_u32_e32 v188, 0, v23
	global_load_dwordx4 v[8:11], v[8:9], off
	v_add_u32_e32 v194, 0, v21
	global_load_dwordx4 v[12:15], v[12:13], off
	v_add_u32_e32 v196, 0, v20
	global_load_dwordx4 v[16:19], v[16:17], off
	v_add_u32_e32 v198, 0, v22
	v_add_u32_e32 v184, 0, v24
	s_waitcnt vmcnt(0)
; #define SLOAD(i, j) do { const long rb_ = KROW(j); sr_[i].vs0 = *(const bf16x8*)(a.V + (rb_ + sr) * LDV + sc); sr_[i].vs1 = *(const bf16x8*)(a.V + (rb_ + 32 + sr) * LDV + sc); \
;     _Pragma("unroll") for (int c_ = 0; c_ < KCH; ++c_) sr_[i].ks[c_] = *(const bf16x8*)(kptr[c_] + rb_ * kld[c_]); } while (0)
; #define SWRITE(b, i) do { *(bf16x8*)(V_lds + (b) * SHM_V + vst0) = sr_[i].vs0; *(bf16x8*)(V_lds + (b) * SHM_V + vst1) = sr_[i].vs1; \
;     _Pragma("unroll") for (int c_ = 0; c_ < KCH; ++c_) *(bf16x8*)(K_lds + (b) * SHM_K + kwo[c_]) = sr_[i].ks[c_]; } while (0)
; template <int DQK, int DK1, int LDQ, int LDK, int LDKR, int LDV, int NQL, int SDEPTH>
; __device__ __forceinline__ void attn_core(const AttnArgs& a, char* lds, f32x16 (&o)[4]) {
;     ...
;     SLOAD(SE, 0); asm volatile("s_waitcnt vmcnt(0)" ::: "memory"); SWRITE(0, SE); __syncthreads();
;     QKT(pA0, pA1, K_lds); partialSM(pA0, pA1, m_reg, mnA, alA, a.C, a.thr);
	v_add_u32_e32 v192, 0, v50
	v_add_u32_e32 v190, 0, v62
	v_add_u32_e32 v173, 0, v63
	s_mov_b32 s37, s36
	s_mov_b32 s38, s36
	s_mov_b32 s39, s36
	s_mov_b32 s40, s36
	s_mov_b32 s41, s36
	s_mov_b32 s42, s36
	s_mov_b32 s43, s36
	s_mov_b32 s44, s36
	s_mov_b32 s45, s36
	s_mov_b32 s46, s36
	s_mov_b32 s47, s36
	s_mov_b32 s48, s36
	s_mov_b32 s49, s36
	s_mov_b32 s50, s36
	s_mov_b32 s51, s36
	v_lshl_add_u32 v165, v51, 2, v161
	v_lshl_add_u64 v[178:179], s[14:15], 0, v[48:49]
	s_mov_b32 s69, 2
	v_add_u32_e32 v216, 0xe000, v184
	v_add_u32_e32 v208, 0xe000, v192
	v_add_u32_e32 v206, 0xe000, v190
	v_add_u32_e32 v202, 0xe000, v173
	v_mov_b32_e32 v182, 0
	s_waitcnt vmcnt(0)
	ds_write_b128 v181, v[64:67]
	ds_write_b128 v181, v[68:71] offset:8192
	ds_write_b128 v181, v[72:75] offset:16384
	ds_write_b128 v181, v[76:79] offset:24576
	ds_write_b128 v186, v[0:3]
	ds_write_b128 v188, v[4:7]
	ds_write_b128 v194, v[8:11] offset:32768
	ds_write_b128 v196, v[12:15] offset:32768
	v_mov_b64_e32 v[0:1], s[36:37]
	ds_write_b128 v198, v[16:19] offset:32768
	s_waitcnt lgkmcnt(0)
	s_barrier
	ds_read_b128 v[16:19], v184 offset:32768
	ds_read_b128 v[20:23], v184 offset:45056
	s_waitcnt lgkmcnt(1)
	v_mfma_f32_32x32x16_bf16 v[32:47], v[16:19], v[126:129], 0
	ds_read_b128 v[54:57], v192 offset:32768
	ds_read_b128 v[58:61], v192 offset:45056
	v_mov_b64_e32 v[14:15], s[50:51]
	v_mov_b64_e32 v[2:3], s[38:39]
	v_mov_b64_e32 v[4:5], s[40:41]
	v_mov_b64_e32 v[6:7], s[42:43]
	v_mov_b64_e32 v[8:9], s[44:45]
	v_mov_b64_e32 v[10:11], s[46:47]
	s_waitcnt lgkmcnt(2)
	v_mfma_f32_32x32x16_bf16 v[16:31], v[20:23], v[126:129], 0
	v_mov_b64_e32 v[12:13], s[48:49]
	s_movk_i32 s37, 0x80
	s_waitcnt lgkmcnt(1)
	v_mfma_f32_32x32x16_bf16 v[32:47], v[54:57], v[122:125], v[32:47]
	s_waitcnt lgkmcnt(0)
	v_mfma_f32_32x32x16_bf16 v[16:31], v[58:61], v[122:125], v[16:31]
	ds_read_b128 v[54:57], v190 offset:32768
	ds_read_b128 v[58:61], v190 offset:45056
	s_waitcnt lgkmcnt(1)
	v_mfma_f32_32x32x16_bf16 v[32:47], v[54:57], v[118:121], v[32:47]
	s_waitcnt lgkmcnt(0)
	v_mfma_f32_32x32x16_bf16 v[16:31], v[58:61], v[118:121], v[16:31]
	ds_read_b128 v[54:57], v173 offset:32768
	ds_read_b128 v[58:61], v173 offset:45056
	s_waitcnt lgkmcnt(1)
	v_mfma_f32_32x32x16_bf16 v[32:47], v[54:57], v[114:117], v[32:47]
	s_waitcnt lgkmcnt(0)
	v_mfma_f32_32x32x16_bf16 v[16:31], v[58:61], v[114:117], v[16:31]
	ds_read_b128 v[54:57], v184 offset:32896
	ds_read_b128 v[58:61], v184 offset:45184
	s_waitcnt lgkmcnt(1)
	v_mfma_f32_32x32x16_bf16 v[32:47], v[54:57], v[110:113], v[32:47]
	s_waitcnt lgkmcnt(0)
	v_mfma_f32_32x32x16_bf16 v[16:31], v[58:61], v[110:113], v[16:31]
	ds_read_b128 v[54:57], v192 offset:32896
	ds_read_b128 v[58:61], v192 offset:45184
	s_waitcnt lgkmcnt(1)
	v_mfma_f32_32x32x16_bf16 v[32:47], v[54:57], v[106:109], v[32:47]
	s_waitcnt lgkmcnt(0)
	v_mfma_f32_32x32x16_bf16 v[16:31], v[58:61], v[106:109], v[16:31]
	ds_read_b128 v[54:57], v190 offset:32896
	ds_read_b128 v[58:61], v190 offset:45184
	s_waitcnt lgkmcnt(1)
	v_mfma_f32_32x32x16_bf16 v[32:47], v[54:57], v[102:105], v[32:47]
	s_waitcnt lgkmcnt(0)
	v_mfma_f32_32x32x16_bf16 v[16:31], v[58:61], v[102:105], v[16:31]
	ds_read_b128 v[54:57], v173 offset:32896
	ds_read_b128 v[58:61], v173 offset:45184
	s_waitcnt lgkmcnt(1)
	v_mfma_f32_32x32x16_bf16 v[32:47], v[54:57], v[98:101], v[32:47]
	s_waitcnt lgkmcnt(0)
	v_mfma_f32_32x32x16_bf16 v[16:31], v[58:61], v[98:101], v[16:31]
	ds_read_b128 v[54:57], v184 offset:33024
	ds_read_b128 v[58:61], v184 offset:45312
	ds_read_b128 v[62:65], v181
	s_waitcnt lgkmcnt(0)
	v_mfma_f32_32x32x16_bf16 v[32:47], v[54:57], v[62:65], v[32:47]
	v_mfma_f32_32x32x16_bf16 v[16:31], v[58:61], v[62:65], v[16:31]
	ds_read_b128 v[54:57], v192 offset:33024
	ds_read_b128 v[58:61], v192 offset:45312
	ds_read_b128 v[62:65], v181 offset:8192
	s_waitcnt lgkmcnt(0)
	v_mfma_f32_32x32x16_bf16 v[32:47], v[54:57], v[62:65], v[32:47]
	v_mfma_f32_32x32x16_bf16 v[16:31], v[58:61], v[62:65], v[16:31]
	ds_read_b128 v[54:57], v190 offset:33024
	ds_read_b128 v[58:61], v190 offset:45312
	ds_read_b128 v[62:65], v181 offset:16384
	s_waitcnt lgkmcnt(0)
	v_mfma_f32_32x32x16_bf16 v[32:47], v[54:57], v[62:65], v[32:47]
	v_mfma_f32_32x32x16_bf16 v[16:31], v[58:61], v[62:65], v[16:31]
	ds_read_b128 v[54:57], v173 offset:33024
	ds_read_b128 v[58:61], v173 offset:45312
	ds_read_b128 v[62:65], v181 offset:24576
	s_waitcnt lgkmcnt(0)
; #define SLOAD(i, j) do { const long rb_ = KROW(j); sr_[i].vs0 = *(const bf16x8*)(a.V + (rb_ + sr) * LDV + sc); sr_[i].vs1 = *(const bf16x8*)(a.V + (rb_ + 32 + sr) * LDV + sc); \
;     _Pragma("unroll") for (int c_ = 0; c_ < KCH; ++c_) sr_[i].ks[c_] = *(const bf16x8*)(kptr[c_] + rb_ * kld[c_]); } while (0)
; #define SWRITE(b, i) do { *(bf16x8*)(V_lds + (b) * SHM_V + vst0) = sr_[i].vs0; *(bf16x8*)(V_lds + (b) * SHM_V + vst1) = sr_[i].vs1; \
;     _Pragma("unroll") for (int c_ = 0; c_ < KCH; ++c_) *(bf16x8*)(K_lds + (b) * SHM_K + kwo[c_]) = sr_[i].ks[c_]; } while (0)
; __device__ __forceinline__ void partialSM(f32x16& p0, f32x16& p1, float& m_reg, float& mn, float& alpha, const float C, const float thr) {
;     float pmax = p0[0];
; #pragma unroll
;     for (int r = 1; r < 16; ++r) pmax = fmaxf(pmax, p0[r]);
; #pragma unroll
;     for (int r = 0; r < 16; ++r) pmax = fmaxf(pmax, p1[r]);
;     { auto rr = __builtin_amdgcn_permlane32_swap(__float_as_uint(pmax), __float_as_uint(pmax), false, false);
;       pmax = fmaxf(__uint_as_float(rr[0]), __uint_as_float(rr[1])); }
;     if (__builtin_expect(__all(pmax - m_reg <= thr), 1)) { mn = m_reg; alpha = 1.f; }
;     else { mn = fmaxf(m_reg, pmax); alpha = __builtin_amdgcn_exp2f((m_reg - mn) * C); m_reg = mn; }
;     const float mnC = -mn * C;
; #pragma unroll
;     for (int r = 0; r < 16; ++r) p0[r] = fmaf(p0[r], C, mnC);
; #pragma unroll
;     for (int r = 0; r < 16; ++r) p1[r] = fmaf(p1[r], C, mnC);
; template <int DQK, int DK1, int LDQ, int LDK, int LDKR, int LDV, int NQL, int SDEPTH>
; __device__ __forceinline__ void attn_core(const AttnArgs& a, char* lds, f32x16 (&o)[4]) {
;     ...
;     SLOAD(SO, 1); if (SDEPTH == 2 && 2 < NT) SLOAD(SE, 2);
;     SWRITE(1, SO); __syncthreads();
	v_mfma_f32_32x32x16_bf16 v[32:47], v[54:57], v[62:65], v[32:47]
	v_mfma_f32_32x32x16_bf16 v[16:31], v[58:61], v[62:65], v[16:31]
	s_nop 10
	v_max_f32_e32 v50, v33, v33
	v_max_f32_e32 v54, v32, v32
	v_max_f32_e32 v50, v54, v50
	v_max3_f32 v50, v50, v34, v35
	v_max3_f32 v50, v50, v36, v37
	v_max3_f32 v50, v50, v38, v39
	v_max3_f32 v50, v50, v40, v41
	v_max3_f32 v50, v50, v42, v43
	v_max3_f32 v50, v50, v44, v45
	v_max3_f32 v50, v50, v46, v47
	v_max3_f32 v50, v50, v16, v17
	v_max3_f32 v50, v50, v18, v19
	v_max3_f32 v50, v50, v20, v21
	v_max3_f32 v50, v50, v22, v23
	v_max3_f32 v50, v50, v24, v25
	v_max3_f32 v50, v50, v26, v27
	v_max3_f32 v50, v50, v28, v29
	v_max3_f32 v50, v50, v30, v31
	v_mov_b32_e32 v54, v50
	s_nop 1
	v_permlane32_swap_b32_e32 v50, v54
	v_max_f32_e32 v54, v54, v54
	v_max_f32_e32 v50, v50, v50
	v_max_f32_e32 v50, v50, v54
	v_add_f32_e32 v54, 0x7149f2ca, v50
	v_cmp_ge_f32_e32 vcc, s72, v54
	s_cmp_eq_u64 vcc, exec
	s_cselect_b64 vcc, -1, 0
	v_max_f32_e32 v50, 0xf149f2ca, v50
	v_cndmask_b32_e32 v204, v50, v193, vcc
	v_sub_f32_e32 v54, 0xf149f2ca, v50
	v_mul_f32_e32 v50, 0xbdd53b94, v204
	s_or_b32 s12, s12, 64
	v_fmamk_f32 v32, v32, 0x3dd53b94, v50
	v_fmamk_f32 v33, v33, 0x3dd53b94, v50
	s_ashr_i32 s13, s12, 31
	v_fmamk_f32 v36, v36, 0x3dd53b94, v50
	v_fmamk_f32 v37, v37, 0x3dd53b94, v50
	v_exp_f32_e32 v219, v32
	v_exp_f32_e32 v221, v33
	v_lshl_add_u64 v[32:33], v[174:175], 0, s[12:13]
	v_exp_f32_e32 v156, v36
	v_exp_f32_e32 v218, v37
	v_lshlrev_b64 v[32:33], 12, v[32:33]
	v_lshl_add_u64 v[36:37], v[176:177], 0, s[12:13]
	v_lshl_add_u64 v[32:33], s[14:15], 0, v[32:33]
	v_lshlrev_b64 v[36:37], 12, v[36:37]
	v_fmamk_f32 v34, v34, 0x3dd53b94, v50
	v_fmamk_f32 v35, v35, 0x3dd53b94, v50
	v_fmamk_f32 v40, v40, 0x3dd53b94, v50
	v_fmamk_f32 v41, v41, 0x3dd53b94, v50
	v_lshl_add_u64 v[32:33], v[32:33], 0, v[48:49]
	v_lshl_add_u64 v[36:37], s[14:15], 0, v[36:37]
	v_fmamk_f32 v38, v38, 0x3dd53b94, v50
	v_fmamk_f32 v39, v39, 0x3dd53b94, v50
	v_fmamk_f32 v44, v44, 0x3dd53b94, v50
	v_fmamk_f32 v45, v45, 0x3dd53b94, v50
	v_exp_f32_e32 v157, v34
	v_exp_f32_e32 v220, v35
	v_exp_f32_e32 v151, v40
	v_exp_f32_e32 v153, v41
	global_load_dwordx4 v[32:35], v[32:33], off offset:256
	v_lshl_add_u64 v[36:37], v[36:37], 0, v[48:49]
	v_mad_i64_i32 v[40:41], s[20:21], v164, s12, 0
	v_fmamk_f32 v42, v42, 0x3dd53b94, v50
	v_fmamk_f32 v43, v43, 0x3dd53b94, v50
	v_exp_f32_e32 v154, v38
	v_exp_f32_e32 v155, v39
	v_exp_f32_e32 v147, v44
	v_exp_f32_e32 v149, v45
	global_load_dwordx4 v[36:39], v[36:37], off offset:256
	v_lshl_add_u64 v[40:41], v[40:41], 1, v[162:163]
	v_mad_i64_i32 v[44:45], s[20:21], v168, s12, 0
	v_mul_f32_e32 v58, 0x3dd53b94, v54
	v_fmamk_f32 v46, v46, 0x3dd53b94, v50
	v_fmamk_f32 v47, v47, 0x3dd53b94, v50
	v_exp_f32_e32 v150, v42
	v_exp_f32_e32 v152, v43
	global_load_dwordx4 v[40:43], v[40:41], off
	v_lshl_add_u64 v[44:45], v[44:45], 1, v[166:167]
	v_mad_i64_i32 v[54:55], s[12:13], v172, s12, 0
	v_exp_f32_e32 v146, v46
	v_exp_f32_e32 v148, v47
	global_load_dwordx4 v[44:47], v[44:45], off
	v_lshl_add_u64 v[54:55], v[54:55], 1, v[170:171]
	global_load_dwordx4 v[54:57], v[54:55], off
	v_exp_f32_e32 v58, v58
	s_cmp_lg_u32 0, -1
	s_cselect_b32 s20, 0, 0
	v_add_u32_e32 v200, s20, v53
	s_addk_i32 s20, 0x4000
	s_waitcnt vmcnt(4)
	ds_write_b128 v186, v[32:35] offset:16384
	s_waitcnt vmcnt(3)
	ds_write_b128 v188, v[36:39] offset:16384
	s_waitcnt vmcnt(2)
	ds_write_b128 v194, v[40:43] offset:57344
	s_waitcnt vmcnt(1)
	ds_write_b128 v196, v[44:47] offset:57344
	s_waitcnt vmcnt(0)
	ds_write_b128 v198, v[54:57] offset:57344
	v_cndmask_b32_e64 v217, v58, 1.0, vcc
	v_pk_fma_f32 v[136:137], v[30:31], s[60:61], v[50:51] op_sel_hi:[1,0,0]
	v_pk_fma_f32 v[138:139], v[28:29], s[60:61], v[50:51] op_sel_hi:[1,0,0]
	v_pk_fma_f32 v[144:145], v[26:27], s[60:61], v[50:51] op_sel_hi:[1,0,0]
	v_pk_fma_f32 v[130:131], v[24:25], s[60:61], v[50:51] op_sel_hi:[1,0,0]
	v_pk_fma_f32 v[132:133], v[22:23], s[60:61], v[50:51] op_sel_hi:[1,0,0]
	v_pk_fma_f32 v[134:135], v[20:21], s[60:61], v[50:51] op_sel_hi:[1,0,0]
	v_pk_fma_f32 v[140:141], v[18:19], s[60:61], v[50:51] op_sel_hi:[1,0,0]
	v_pk_fma_f32 v[142:143], v[16:17], s[60:61], v[50:51] op_sel_hi:[1,0,0]
	v_cmp_gt_u32_e64 s[12:13], 32, v52
	v_add_u32_e32 v169, s20, v53
	v_mov_b64_e32 v[30:31], v[14:15]
	v_mov_b64_e32 v[46:47], v[14:15]
	v_mov_b64_e32 v[62:63], v[14:15]
	v_mov_b64_e32 v[28:29], v[12:13]
	v_mov_b64_e32 v[26:27], v[10:11]
	v_mov_b64_e32 v[24:25], v[8:9]
	v_mov_b64_e32 v[22:23], v[6:7]
	v_mov_b64_e32 v[20:21], v[4:5]
	v_mov_b64_e32 v[18:19], v[2:3]
	v_mov_b64_e32 v[16:17], v[0:1]
	v_mov_b64_e32 v[44:45], v[12:13]
	v_mov_b64_e32 v[42:43], v[10:11]
	v_mov_b64_e32 v[40:41], v[8:9]
	v_mov_b64_e32 v[38:39], v[6:7]
	v_mov_b64_e32 v[36:37], v[4:5]
	v_mov_b64_e32 v[34:35], v[2:3]
	v_mov_b64_e32 v[32:33], v[0:1]
	v_mov_b64_e32 v[60:61], v[12:13]
	v_mov_b64_e32 v[58:59], v[10:11]
	v_mov_b64_e32 v[56:57], v[8:9]
	v_mov_b64_e32 v[54:55], v[6:7]
	v_mov_b64_e32 v[52:53], v[4:5]
	v_mov_b64_e32 v[50:51], v[2:3]
	v_mov_b64_e32 v[48:49], v[0:1]
	s_waitcnt lgkmcnt(0)
	s_barrier
